# baseline (speedup 1.0000x reference)
; #define WAIT_V(n) asm volatile("s_waitcnt vmcnt(" #n ")" ::: "memory")
; #define BAR __builtin_amdgcn_s_barrier()
;     ...
;     f32x4 acc[2][2][4][2] = {};
;     bf16x8 At[4][2], B0[2][2], B1[2][2];
;     STAGE(SB(0, 0), Bt, bcol, 0); STAGE(SA(0, 0), A, brow, 0);
;     STAGE(SB(0, 1), Bt, bcol + HALF, 0); STAGE(SA(0, 1), A, brow + HALF, 0);
;     if (wr == 1) BAR;
;     WAIT_V(4); BAR;
;     STAGE(SB(1, 0), Bt, bcol, 1); STAGE(SA(1, 0), A, brow, 1); STAGE(SB(1, 1), Bt, bcol + HALF, 1);
;     WAIT_V(6); BAR;
.LBB0_97:
	s_or_b32 s34, s48, 1
	s_mov_b32 s35, s49
	s_lshl_b64 s[42:43], s[34:35], 6
	s_add_u32 s34, s42, s6
	s_addc_u32 s35, s43, s4
	s_lshl_b64 s[34:35], s[34:35], 1
	s_add_u32 s44, s24, s34
	s_addc_u32 s45, s25, s35
	s_add_i32 s34, s15, 0x18000
	s_add_i32 s35, s15, 0x1a000
	s_add_u32 s4, s42, s5
	s_addc_u32 s5, s43, s7
	s_lshl_b64 s[4:5], s[4:5], 1
	v_mov_b32_e32 v141, v1
	s_waitcnt vmcnt(4)
	s_barrier
	s_mov_b32 m0, s34
	v_lshl_add_u64 v[4:5], s[44:45], 0, v[0:1]
	s_add_u32 s4, s22, s4
	global_load_lds_dwordx4 v[4:5], off
	v_lshl_add_u64 v[4:5], s[44:45], 0, v[140:141]
	s_mov_b32 m0, s35
	s_addc_u32 s5, s23, s5
	s_add_i32 s37, s15, 0x8000
	global_load_lds_dwordx4 v[4:5], off
	s_mov_b32 m0, s37
	v_lshl_add_u64 v[4:5], s[4:5], 0, v[0:1]
	s_waitcnt lgkmcnt(0)
	s_add_i32 s38, s15, 0xa000
	global_load_lds_dwordx4 v[4:5], off
	v_lshl_add_u64 v[4:5], s[4:5], 0, v[140:141]
	s_add_u32 s4, s42, s39
	s_addc_u32 s5, s43, s40
	s_lshl_b64 s[4:5], s[4:5], 1
	s_add_u32 s4, s24, s4
	s_mov_b32 m0, s38
	s_addc_u32 s5, s25, s5
	s_add_i32 s41, s15, 0x1c000
	global_load_lds_dwordx4 v[4:5], off
	s_mov_b32 m0, s41
	v_lshl_add_u64 v[4:5], s[4:5], 0, v[0:1]
	s_add_i32 s42, s15, 0x1e000
	global_load_lds_dwordx4 v[4:5], off
	v_lshl_add_u64 v[4:5], s[4:5], 0, v[140:141]
	s_mov_b32 m0, s42
	v_and_b32_e32 v3, 15, v2
	global_load_lds_dwordx4 v[4:5], off
	v_and_b32_e32 v6, 48, v2
	v_lshlrev_b32_e32 v2, 2, v2
	v_lshlrev_b32_e32 v4, 6, v3
	v_and_b32_e32 v2, 32, v2
	v_bitop3_b32 v142, v4, v2, v6 bitop3:0x36
	v_or_b32_e32 v2, s33, v3
	v_lshlrev_b32_e32 v4, 6, v2
	v_lshlrev_b32_e32 v2, 2, v2
	v_and_b32_e32 v4, 0x3c0, v4
	v_and_b32_e32 v2, 32, v2
	v_readlane_b32 s4, v245, 36
	s_add_i32 s43, s14, -2
	s_mul_i32 s40, s29, 0x2c00
	v_bitop3_b32 v4, v4, v2, v6 bitop3:0x36
	v_or_b32_e32 v2, s4, v3
	s_mul_hi_i32 s39, s29, 0x2c00
	s_add_u32 s55, s22, s40
	v_lshlrev_b32_e32 v5, 6, v2
	v_lshlrev_b32_e32 v2, 2, v2
	s_addc_u32 s57, s23, s39
	v_and_b32_e32 v5, 0x3c0, v5
	v_and_b32_e32 v2, 32, v2
	v_readlane_b32 s4, v245, 37
	s_ashr_i32 s7, s6, 31
	v_bitop3_b32 v5, v5, v2, v6 bitop3:0x36
	v_or_b32_e32 v2, s4, v3
	s_lshl_b64 s[4:5], s[48:49], 7
	s_lshl_b64 s[6:7], s[6:7], 1
	s_add_u32 s6, s24, s6
	v_lshlrev_b32_e32 v7, 6, v2
	v_lshlrev_b32_e32 v2, 2, v2
	s_addc_u32 s7, s25, s7
	s_mul_i32 s44, s20, 0x2c00
	v_and_b32_e32 v7, 0x3c0, v7
	v_and_b32_e32 v2, 32, v2
	s_mul_hi_i32 s45, s20, 0x2c00
	s_add_u32 s44, s22, s44
	v_bitop3_b32 v7, v7, v2, v6 bitop3:0x36
	v_or_b32_e32 v2, s85, v3
	s_addc_u32 s45, s23, s45
	s_mul_i32 s50, s10, 0x2c00
	v_readlane_b32 s59, v244, 19
	v_lshlrev_b32_e32 v3, 6, v2
	v_lshlrev_b32_e32 v2, 2, v2
	s_mul_hi_i32 s51, s10, 0x2c00
	s_add_u32 s50, s24, s50
	v_add_u32_e32 v133, s59, v4
	v_readlane_b32 s59, v244, 20
	v_mov_b32_e32 v8, 0
	v_mov_b32_e32 v9, 0
	v_mov_b32_e32 v10, 0
	v_mov_b32_e32 v11, 0
	v_mov_b32_e32 v12, 0
	v_mov_b32_e32 v13, 0
	v_mov_b32_e32 v14, 0
	v_mov_b32_e32 v15, 0
	v_mov_b32_e32 v16, 0
	v_mov_b32_e32 v17, 0
	v_mov_b32_e32 v18, 0
	v_mov_b32_e32 v19, 0
	v_mov_b32_e32 v20, 0
	v_mov_b32_e32 v21, 0
	v_mov_b32_e32 v22, 0
	v_mov_b32_e32 v23, 0
	v_mov_b32_e32 v24, 0
	v_mov_b32_e32 v25, 0
	v_mov_b32_e32 v26, 0
	v_mov_b32_e32 v27, 0
	v_mov_b32_e32 v28, 0
	v_mov_b32_e32 v29, 0
	v_mov_b32_e32 v30, 0
	v_mov_b32_e32 v31, 0
	v_mov_b32_e32 v32, 0
	v_mov_b32_e32 v33, 0
	v_mov_b32_e32 v34, 0
	v_mov_b32_e32 v35, 0
	v_mov_b32_e32 v36, 0
	v_mov_b32_e32 v37, 0
	v_mov_b32_e32 v38, 0
	v_mov_b32_e32 v39, 0
	v_mov_b32_e32 v40, 0
	v_mov_b32_e32 v41, 0
	v_mov_b32_e32 v42, 0
	v_mov_b32_e32 v43, 0
	v_mov_b32_e32 v44, 0
	v_mov_b32_e32 v45, 0
	v_mov_b32_e32 v46, 0
	v_mov_b32_e32 v47, 0
	v_mov_b32_e32 v48, 0
	v_mov_b32_e32 v49, 0
	v_mov_b32_e32 v50, 0
	v_mov_b32_e32 v51, 0
	v_mov_b32_e32 v52, 0
	v_mov_b32_e32 v53, 0
	v_mov_b32_e32 v54, 0
	v_mov_b32_e32 v55, 0
	v_mov_b32_e32 v56, 0
	v_mov_b32_e32 v57, 0
	v_mov_b32_e32 v58, 0
	v_mov_b32_e32 v59, 0
	v_mov_b32_e32 v60, 0
	v_mov_b32_e32 v61, 0
	v_mov_b32_e32 v62, 0
	v_mov_b32_e32 v63, 0
	v_mov_b32_e32 v64, 0
	v_mov_b32_e32 v65, 0
	v_mov_b32_e32 v66, 0
	v_mov_b32_e32 v67, 0
	v_mov_b32_e32 v68, 0
	v_mov_b32_e32 v69, 0
	v_mov_b32_e32 v70, 0
	v_mov_b32_e32 v71, 0
	v_mov_b32_e32 v72, 0
	v_mov_b32_e32 v73, 0
	v_mov_b32_e32 v74, 0
	v_mov_b32_e32 v75, 0
	v_mov_b32_e32 v76, 0
	v_mov_b32_e32 v77, 0
	v_mov_b32_e32 v78, 0
	v_mov_b32_e32 v79, 0
	v_mov_b32_e32 v80, 0
	v_mov_b32_e32 v81, 0
	v_mov_b32_e32 v82, 0
	v_mov_b32_e32 v83, 0
	v_mov_b32_e32 v84, 0
	v_mov_b32_e32 v85, 0
	v_mov_b32_e32 v86, 0
	v_mov_b32_e32 v87, 0
	v_mov_b32_e32 v88, 0
	v_mov_b32_e32 v89, 0
	v_mov_b32_e32 v90, 0
	v_mov_b32_e32 v91, 0
	v_mov_b32_e32 v92, 0
	v_mov_b32_e32 v93, 0
	v_mov_b32_e32 v94, 0
	v_mov_b32_e32 v95, 0
	v_mov_b32_e32 v96, 0
	v_mov_b32_e32 v97, 0
	v_mov_b32_e32 v98, 0
	v_mov_b32_e32 v99, 0
	v_mov_b32_e32 v100, 0
	v_mov_b32_e32 v101, 0
	v_mov_b32_e32 v102, 0
	v_mov_b32_e32 v103, 0
	v_mov_b32_e32 v104, 0
	v_mov_b32_e32 v105, 0
	v_mov_b32_e32 v106, 0
	v_mov_b32_e32 v107, 0
	v_mov_b32_e32 v108, 0
	v_mov_b32_e32 v109, 0
	v_mov_b32_e32 v110, 0
	v_mov_b32_e32 v111, 0
	v_mov_b32_e32 v112, 0
	v_mov_b32_e32 v113, 0
	v_mov_b32_e32 v114, 0
	v_mov_b32_e32 v115, 0
	v_mov_b32_e32 v116, 0
	v_mov_b32_e32 v117, 0
	v_mov_b32_e32 v118, 0
	v_mov_b32_e32 v119, 0
	v_mov_b32_e32 v120, 0
	v_mov_b32_e32 v121, 0
	v_mov_b32_e32 v122, 0
	v_mov_b32_e32 v123, 0
	v_mov_b32_e32 v124, 0
	v_mov_b32_e32 v125, 0
	v_mov_b32_e32 v126, 0
	v_mov_b32_e32 v127, 0
	v_mov_b32_e32 v128, 0
	v_mov_b32_e32 v129, 0
	s_waitcnt vmcnt(6)
	v_and_b32_e32 v3, 0x3c0, v3
	v_and_b32_e32 v2, 32, v2
	s_addc_u32 s51, s25, s51
	v_add_u32_e32 v134, s59, v5
	v_readlane_b32 s59, v244, 21
	v_bitop3_b32 v3, v3, v2, v6 bitop3:0x36
	s_add_u32 s55, s55, 0x80
	v_mov_b32_e32 v2, 0
	v_add_u32_e32 v137, s59, v7
	v_readlane_b32 s59, v244, 22
	s_addc_u32 s57, s57, 0
	s_mov_b32 s58, 0
	v_add_u32_e32 v139, s59, v3
	v_mov_b32_e32 v3, v2
	v_mov_b32_e32 v4, v2
	v_mov_b32_e32 v5, v2
	v_mov_b32_e32 v6, v2
	v_mov_b32_e32 v7, v2
	s_barrier

; #define WAIT_V(n) asm volatile("s_waitcnt vmcnt(" #n ")" ::: "memory")
; #define BAR __builtin_amdgcn_s_barrier()
;     ...
;     f32x4 acc[2][2][4][2] = {};
;     bf16x8 At[4][2], B0[2][2], B1[2][2];
;     STAGE(SB(0, 0), Bt, bcol, 0); STAGE(SA(0, 0), A, brow, 0);
;     STAGE(SB(0, 1), Bt, bcol + HALF, 0); STAGE(SA(0, 1), A, brow + HALF, 0);
;     if (wr == 1) BAR;
;     WAIT_V(4); BAR;
;     STAGE(SB(1, 0), Bt, bcol, 1); STAGE(SA(1, 0), A, brow, 1); STAGE(SB(1, 1), Bt, bcol + HALF, 1);
;     WAIT_V(6); BAR;
.LBB0_154:
	s_add_u32 s34, s12, 0x80
	s_addc_u32 s35, s13, 0
	s_add_i32 s12, s24, 0x18000
	v_mov_b32_e32 v141, v1
	s_waitcnt vmcnt(4)
	s_barrier
	s_mov_b32 m0, s12
	v_lshl_add_u64 v[4:5], s[34:35], 0, v[0:1]
	s_add_i32 s13, s24, 0x1a000
	global_load_lds_dwordx4 v[4:5], off
	v_lshl_add_u64 v[4:5], s[34:35], 0, v[140:141]
	s_add_u32 s34, s14, 0x80
	s_mov_b32 m0, s13
	s_addc_u32 s35, s15, 0
	s_add_i32 s14, s24, 0x8000
	global_load_lds_dwordx4 v[4:5], off
	s_mov_b32 m0, s14
	v_lshl_add_u64 v[4:5], s[34:35], 0, v[0:1]
	s_add_i32 s15, s24, 0xa000
	global_load_lds_dwordx4 v[4:5], off
	v_lshl_add_u64 v[4:5], s[34:35], 0, v[140:141]
	s_add_u32 s34, s16, 0x80
	s_mov_b32 m0, s15
	s_addc_u32 s35, s17, 0
	s_add_i32 s16, s24, 0x1c000
	global_load_lds_dwordx4 v[4:5], off
	s_mov_b32 m0, s16
	v_lshl_add_u64 v[4:5], s[34:35], 0, v[0:1]
	s_add_i32 s17, s24, 0x1e000
	global_load_lds_dwordx4 v[4:5], off
	v_lshl_add_u64 v[4:5], s[34:35], 0, v[140:141]
	s_mov_b32 m0, s17
	v_and_b32_e32 v3, 15, v2
	global_load_lds_dwordx4 v[4:5], off
	v_and_b32_e32 v6, 48, v2
	v_lshlrev_b32_e32 v2, 2, v2
	v_lshlrev_b32_e32 v4, 6, v3
	v_and_b32_e32 v2, 32, v2
	v_bitop3_b32 v142, v4, v2, v6 bitop3:0x36
	v_or_b32_e32 v2, s33, v3
	v_lshlrev_b32_e32 v4, 6, v2
	v_lshlrev_b32_e32 v2, 2, v2
	v_and_b32_e32 v4, 0x3c0, v4
	v_and_b32_e32 v2, 32, v2
	v_readlane_b32 s34, v245, 36
	v_bitop3_b32 v4, v4, v2, v6 bitop3:0x36
	s_lshl_b32 s30, s30, 11
	v_or_b32_e32 v2, s34, v3
	v_lshlrev_b32_e32 v5, 6, v2
	v_lshlrev_b32_e32 v2, 2, v2
	v_and_b32_e32 v5, 0x3c0, v5
	v_and_b32_e32 v2, 32, v2
	v_readlane_b32 s34, v245, 37
	v_bitop3_b32 v5, v5, v2, v6 bitop3:0x36
	s_lshl_b32 s31, s31, 8
	v_or_b32_e32 v2, s34, v3
	v_lshlrev_b32_e32 v7, 6, v2
	v_lshlrev_b32_e32 v2, 2, v2
	s_add_i32 s30, s30, s31
	v_and_b32_e32 v7, 0x3c0, v7
	v_and_b32_e32 v2, 32, v2
	s_ashr_i32 s31, s30, 31
	v_bitop3_b32 v7, v7, v2, v6 bitop3:0x36
	v_or_b32_e32 v2, s85, v3
	s_lshl_b64 s[30:31], s[30:31], 12
	s_waitcnt lgkmcnt(0)
	v_readlane_b32 s38, v244, 19
	v_lshlrev_b32_e32 v3, 6, v2
	v_lshlrev_b32_e32 v2, 2, v2
	s_add_u32 s30, s74, s30
	v_add_u32_e32 v133, s38, v4
	v_readlane_b32 s38, v244, 20
	v_mov_b32_e32 v8, 0
	v_mov_b32_e32 v9, 0
	v_mov_b32_e32 v10, 0
	v_mov_b32_e32 v11, 0
	v_mov_b32_e32 v12, 0
	v_mov_b32_e32 v13, 0
	v_mov_b32_e32 v14, 0
	v_mov_b32_e32 v15, 0
	v_mov_b32_e32 v16, 0
	v_mov_b32_e32 v17, 0
	v_mov_b32_e32 v18, 0
	v_mov_b32_e32 v19, 0
	v_mov_b32_e32 v20, 0
	v_mov_b32_e32 v21, 0
	v_mov_b32_e32 v22, 0
	v_mov_b32_e32 v23, 0
	v_mov_b32_e32 v24, 0
	v_mov_b32_e32 v25, 0
	v_mov_b32_e32 v26, 0
	v_mov_b32_e32 v27, 0
	v_mov_b32_e32 v28, 0
	v_mov_b32_e32 v29, 0
	v_mov_b32_e32 v30, 0
	v_mov_b32_e32 v31, 0
	v_mov_b32_e32 v32, 0
	v_mov_b32_e32 v33, 0
	v_mov_b32_e32 v34, 0
	v_mov_b32_e32 v35, 0
	v_mov_b32_e32 v36, 0
	v_mov_b32_e32 v37, 0
	v_mov_b32_e32 v38, 0
	v_mov_b32_e32 v39, 0
	v_mov_b32_e32 v40, 0
	v_mov_b32_e32 v41, 0
	v_mov_b32_e32 v42, 0
	v_mov_b32_e32 v43, 0
	v_mov_b32_e32 v44, 0
	v_mov_b32_e32 v45, 0
	v_mov_b32_e32 v46, 0
	v_mov_b32_e32 v47, 0
	v_mov_b32_e32 v48, 0
	v_mov_b32_e32 v49, 0
	v_mov_b32_e32 v50, 0
	v_mov_b32_e32 v51, 0
	v_mov_b32_e32 v52, 0
	v_mov_b32_e32 v53, 0
	v_mov_b32_e32 v54, 0
	v_mov_b32_e32 v55, 0
	v_mov_b32_e32 v56, 0
	v_mov_b32_e32 v57, 0
	v_mov_b32_e32 v58, 0
	v_mov_b32_e32 v59, 0
	v_mov_b32_e32 v60, 0
	v_mov_b32_e32 v61, 0
	v_mov_b32_e32 v62, 0
	v_mov_b32_e32 v63, 0
	v_mov_b32_e32 v64, 0
	v_mov_b32_e32 v65, 0
	v_mov_b32_e32 v66, 0
	v_mov_b32_e32 v67, 0
	v_mov_b32_e32 v68, 0
	v_mov_b32_e32 v69, 0
	v_mov_b32_e32 v70, 0
	v_mov_b32_e32 v71, 0
	v_mov_b32_e32 v72, 0
	v_mov_b32_e32 v73, 0
	v_mov_b32_e32 v74, 0
	v_mov_b32_e32 v75, 0
	v_mov_b32_e32 v76, 0
	v_mov_b32_e32 v77, 0
	v_mov_b32_e32 v78, 0
	v_mov_b32_e32 v79, 0
	v_mov_b32_e32 v80, 0
	v_mov_b32_e32 v81, 0
	v_mov_b32_e32 v82, 0
	v_mov_b32_e32 v83, 0
	v_mov_b32_e32 v84, 0
	v_mov_b32_e32 v85, 0
	v_mov_b32_e32 v86, 0
	v_mov_b32_e32 v87, 0
	v_mov_b32_e32 v88, 0
	v_mov_b32_e32 v89, 0
	v_mov_b32_e32 v90, 0
	v_mov_b32_e32 v91, 0
	v_mov_b32_e32 v92, 0
	v_mov_b32_e32 v93, 0
	v_mov_b32_e32 v94, 0
	v_mov_b32_e32 v95, 0
	v_mov_b32_e32 v96, 0
	v_mov_b32_e32 v97, 0
	v_mov_b32_e32 v98, 0
	v_mov_b32_e32 v99, 0
	v_mov_b32_e32 v100, 0
	v_mov_b32_e32 v101, 0
	v_mov_b32_e32 v102, 0
	v_mov_b32_e32 v103, 0
	v_mov_b32_e32 v104, 0
	v_mov_b32_e32 v105, 0
	v_mov_b32_e32 v106, 0
	v_mov_b32_e32 v107, 0
	v_mov_b32_e32 v108, 0
	v_mov_b32_e32 v109, 0
	v_mov_b32_e32 v110, 0
	v_mov_b32_e32 v111, 0
	v_mov_b32_e32 v112, 0
	v_mov_b32_e32 v113, 0
	v_mov_b32_e32 v114, 0
	v_mov_b32_e32 v115, 0
	v_mov_b32_e32 v116, 0
	v_mov_b32_e32 v117, 0
	v_mov_b32_e32 v118, 0
	v_mov_b32_e32 v119, 0
	v_mov_b32_e32 v120, 0
	v_mov_b32_e32 v121, 0
	v_mov_b32_e32 v122, 0
	v_mov_b32_e32 v123, 0
	v_mov_b32_e32 v124, 0
	v_mov_b32_e32 v125, 0
	v_mov_b32_e32 v126, 0
	v_mov_b32_e32 v127, 0
	v_mov_b32_e32 v128, 0
	v_mov_b32_e32 v129, 0
	s_waitcnt vmcnt(6)
	v_and_b32_e32 v3, 0x3c0, v3
	v_and_b32_e32 v2, 32, v2
	s_addc_u32 s31, s75, s31
	v_add_u32_e32 v134, s38, v5
	v_readlane_b32 s38, v244, 21
	v_bitop3_b32 v3, v3, v2, v6 bitop3:0x36
	s_add_u32 s34, s18, s10
	v_mov_b32_e32 v2, 0
	v_add_u32_e32 v137, s38, v7
	v_readlane_b32 s38, v244, 22
	s_addc_u32 s35, s19, s11
	s_mov_b32 s37, -2
	s_mov_b64 s[10:11], 0
	v_add_u32_e32 v139, s38, v3
	v_mov_b32_e32 v3, v2
	v_mov_b32_e32 v4, v2
	v_mov_b32_e32 v5, v2
	v_mov_b32_e32 v6, v2
	v_mov_b32_e32 v7, v2
	s_barrier

; #define WAIT_V(n) asm volatile("s_waitcnt vmcnt(" #n ")" ::: "memory")
; #define BAR __builtin_amdgcn_s_barrier()
;     ...
;     f32x4 acc[2][2][4][2] = {};
;     bf16x8 At[4][2], B0[2][2], B1[2][2];
;     STAGE(SB(0, 0), Bt, bcol, 0); STAGE(SA(0, 0), A, brow, 0);
;     STAGE(SB(0, 1), Bt, bcol + HALF, 0); STAGE(SA(0, 1), A, brow + HALF, 0);
;     if (wr == 1) BAR;
;     WAIT_V(4); BAR;
;     STAGE(SB(1, 0), Bt, bcol, 1); STAGE(SA(1, 0), A, brow, 1); STAGE(SB(1, 1), Bt, bcol + HALF, 1);
;     WAIT_V(6); BAR;
.LBB0_201:
	s_or_b32 s40, s48, 1
	s_mov_b32 s41, s49
	s_lshl_b64 s[44:45], s[40:41], 6
	s_add_u32 s4, s44, s4
	s_addc_u32 s5, s45, s5
	s_lshl_b64 s[4:5], s[4:5], 1
	s_add_u32 s4, s22, s4
	s_addc_u32 s5, s23, s5
	s_add_i32 s39, s21, 0x18000
	v_mov_b32_e32 v141, v1
	s_waitcnt vmcnt(4)
	s_barrier
	s_mov_b32 m0, s39
	v_lshl_add_u64 v[4:5], s[4:5], 0, v[0:1]
	s_add_i32 s40, s21, 0x1a000
	global_load_lds_dwordx4 v[4:5], off
	v_lshl_add_u64 v[4:5], s[4:5], 0, v[140:141]
	s_add_u32 s4, s44, s16
	s_addc_u32 s5, s45, s17
	s_lshl_b64 s[4:5], s[4:5], 1
	s_add_u32 s4, s74, s4
	s_mov_b32 m0, s40
	s_addc_u32 s5, s75, s5
	s_add_i32 s41, s21, 0x8000
	global_load_lds_dwordx4 v[4:5], off
	s_mov_b32 m0, s41
	v_lshl_add_u64 v[4:5], s[4:5], 0, v[0:1]
	s_add_i32 s42, s21, 0xa000
	global_load_lds_dwordx4 v[4:5], off
	v_lshl_add_u64 v[4:5], s[4:5], 0, v[140:141]
	s_add_u32 s4, s44, s18
	s_addc_u32 s5, s45, s19
	s_lshl_b64 s[4:5], s[4:5], 1
	s_add_u32 s4, s22, s4
	s_mov_b32 m0, s42
	s_addc_u32 s5, s23, s5
	s_add_i32 s18, s21, 0x1c000
	global_load_lds_dwordx4 v[4:5], off
	s_mov_b32 m0, s18
	v_lshl_add_u64 v[4:5], s[4:5], 0, v[0:1]
	s_add_i32 s19, s21, 0x1e000
	global_load_lds_dwordx4 v[4:5], off
	v_lshl_add_u64 v[4:5], s[4:5], 0, v[140:141]
	s_mov_b32 m0, s19
	v_and_b32_e32 v3, 15, v2
	global_load_lds_dwordx4 v[4:5], off
	v_and_b32_e32 v6, 48, v2
	v_lshlrev_b32_e32 v2, 2, v2
	v_lshlrev_b32_e32 v4, 6, v3
	v_and_b32_e32 v2, 32, v2
	v_bitop3_b32 v142, v4, v2, v6 bitop3:0x36
	v_or_b32_e32 v2, s33, v3
	v_lshlrev_b32_e32 v4, 6, v2
	v_lshlrev_b32_e32 v2, 2, v2
	s_lshl_b64 s[4:5], s[10:11], 12
	v_and_b32_e32 v4, 0x3c0, v4
	v_and_b32_e32 v2, 32, v2
	v_readlane_b32 s11, v245, 36
	s_add_i32 s43, s20, -2
	v_bitop3_b32 v4, v4, v2, v6 bitop3:0x36
	v_or_b32_e32 v2, s11, v3
	s_add_u32 s55, s74, s4
	v_lshlrev_b32_e32 v5, 6, v2
	v_lshlrev_b32_e32 v2, 2, v2
	s_addc_u32 s57, s75, s5
	v_and_b32_e32 v5, 0x3c0, v5
	v_and_b32_e32 v2, 32, v2
	v_readlane_b32 s11, v245, 37
	s_lshl_b64 s[16:17], s[48:49], 7
	s_lshl_b64 s[44:45], s[14:15], 12
	v_bitop3_b32 v5, v5, v2, v6 bitop3:0x36
	v_or_b32_e32 v2, s11, v3
	s_add_u32 s11, s22, s44
	s_addc_u32 s44, s23, s45
	s_lshl_b64 s[50:51], s[12:13], 12
	s_add_u32 s13, s74, s50
	v_lshlrev_b32_e32 v7, 6, v2
	v_lshlrev_b32_e32 v2, 2, v2
	s_addc_u32 s45, s75, s51
	v_and_b32_e32 v7, 0x3c0, v7
	v_and_b32_e32 v2, 32, v2
	s_add_u32 s50, s55, 0x80
	v_bitop3_b32 v7, v7, v2, v6 bitop3:0x36
	v_or_b32_e32 v2, s85, v3
	s_addc_u32 s51, s57, 0
	v_readlane_b32 s57, v244, 19
	v_lshlrev_b32_e32 v3, 6, v2
	v_lshlrev_b32_e32 v2, 2, v2
	v_add_u32_e32 v133, s57, v4
	v_readlane_b32 s57, v244, 20
	v_mov_b32_e32 v8, 0
	v_mov_b32_e32 v9, 0
	v_mov_b32_e32 v10, 0
	v_mov_b32_e32 v11, 0
	v_mov_b32_e32 v12, 0
	v_mov_b32_e32 v13, 0
	v_mov_b32_e32 v14, 0
	v_mov_b32_e32 v15, 0
	v_mov_b32_e32 v16, 0
	v_mov_b32_e32 v17, 0
	v_mov_b32_e32 v18, 0
	v_mov_b32_e32 v19, 0
	v_mov_b32_e32 v20, 0
	v_mov_b32_e32 v21, 0
	v_mov_b32_e32 v22, 0
	v_mov_b32_e32 v23, 0
	v_mov_b32_e32 v24, 0
	v_mov_b32_e32 v25, 0
	v_mov_b32_e32 v26, 0
	v_mov_b32_e32 v27, 0
	v_mov_b32_e32 v28, 0
	v_mov_b32_e32 v29, 0
	v_mov_b32_e32 v30, 0
	v_mov_b32_e32 v31, 0
	v_mov_b32_e32 v32, 0
	v_mov_b32_e32 v33, 0
	v_mov_b32_e32 v34, 0
	v_mov_b32_e32 v35, 0
	v_mov_b32_e32 v36, 0
	v_mov_b32_e32 v37, 0
	v_mov_b32_e32 v38, 0
	v_mov_b32_e32 v39, 0
	v_mov_b32_e32 v40, 0
	v_mov_b32_e32 v41, 0
	v_mov_b32_e32 v42, 0
	v_mov_b32_e32 v43, 0
	v_mov_b32_e32 v44, 0
	v_mov_b32_e32 v45, 0
	v_mov_b32_e32 v46, 0
	v_mov_b32_e32 v47, 0
	v_mov_b32_e32 v48, 0
	v_mov_b32_e32 v49, 0
	v_mov_b32_e32 v50, 0
	v_mov_b32_e32 v51, 0
	v_mov_b32_e32 v52, 0
	v_mov_b32_e32 v53, 0
	v_mov_b32_e32 v54, 0
	v_mov_b32_e32 v55, 0
	v_mov_b32_e32 v56, 0
	v_mov_b32_e32 v57, 0
	v_mov_b32_e32 v58, 0
	v_mov_b32_e32 v59, 0
	v_mov_b32_e32 v60, 0
	v_mov_b32_e32 v61, 0
	v_mov_b32_e32 v62, 0
	v_mov_b32_e32 v63, 0
	v_mov_b32_e32 v64, 0
	v_mov_b32_e32 v65, 0
	v_mov_b32_e32 v66, 0
	v_mov_b32_e32 v67, 0
	v_mov_b32_e32 v68, 0
	v_mov_b32_e32 v69, 0
	v_mov_b32_e32 v70, 0
	v_mov_b32_e32 v71, 0
	v_mov_b32_e32 v72, 0
	v_mov_b32_e32 v73, 0
	v_mov_b32_e32 v74, 0
	v_mov_b32_e32 v75, 0
	v_mov_b32_e32 v76, 0
	v_mov_b32_e32 v77, 0
	v_mov_b32_e32 v78, 0
	v_mov_b32_e32 v79, 0
	v_mov_b32_e32 v80, 0
	v_mov_b32_e32 v81, 0
	v_mov_b32_e32 v82, 0
	v_mov_b32_e32 v83, 0
	v_mov_b32_e32 v84, 0
	v_mov_b32_e32 v85, 0
	v_mov_b32_e32 v86, 0
	v_mov_b32_e32 v87, 0
	v_mov_b32_e32 v88, 0
	v_mov_b32_e32 v89, 0
	v_mov_b32_e32 v90, 0
	v_mov_b32_e32 v91, 0
	v_mov_b32_e32 v92, 0
	v_mov_b32_e32 v93, 0
	v_mov_b32_e32 v94, 0
	v_mov_b32_e32 v95, 0
	v_mov_b32_e32 v96, 0
	v_mov_b32_e32 v97, 0
	v_mov_b32_e32 v98, 0
	v_mov_b32_e32 v99, 0
	v_mov_b32_e32 v100, 0
	v_mov_b32_e32 v101, 0
	v_mov_b32_e32 v102, 0
	v_mov_b32_e32 v103, 0
	v_mov_b32_e32 v104, 0
	v_mov_b32_e32 v105, 0
	v_mov_b32_e32 v106, 0
	v_mov_b32_e32 v107, 0
	v_mov_b32_e32 v108, 0
	v_mov_b32_e32 v109, 0
	v_mov_b32_e32 v110, 0
	v_mov_b32_e32 v111, 0
	v_mov_b32_e32 v112, 0
	v_mov_b32_e32 v113, 0
	v_mov_b32_e32 v114, 0
	v_mov_b32_e32 v115, 0
	v_mov_b32_e32 v116, 0
	v_mov_b32_e32 v117, 0
	v_mov_b32_e32 v118, 0
	v_mov_b32_e32 v119, 0
	v_mov_b32_e32 v120, 0
	v_mov_b32_e32 v121, 0
	v_mov_b32_e32 v122, 0
	v_mov_b32_e32 v123, 0
	v_mov_b32_e32 v124, 0
	v_mov_b32_e32 v125, 0
	v_mov_b32_e32 v126, 0
	v_mov_b32_e32 v127, 0
	v_mov_b32_e32 v128, 0
	v_mov_b32_e32 v129, 0
	s_waitcnt vmcnt(6)
	v_and_b32_e32 v3, 0x3c0, v3
	v_and_b32_e32 v2, 32, v2
	v_add_u32_e32 v134, s57, v5
	v_readlane_b32 s57, v244, 21
	v_bitop3_b32 v3, v3, v2, v6 bitop3:0x36
	v_mov_b32_e32 v2, 0
	v_add_u32_e32 v137, s57, v7
	v_readlane_b32 s57, v244, 22
	s_mov_b32 s55, 0
	v_mov_b32_e32 v4, v2
	v_add_u32_e32 v139, s57, v3
	v_mov_b32_e32 v3, v2
	v_mov_b32_e32 v5, v2
	v_mov_b32_e32 v6, v2
	v_mov_b32_e32 v7, v2
	s_barrier

; #define WAIT_V(n) asm volatile("s_waitcnt vmcnt(" #n ")" ::: "memory")
; #define BAR __builtin_amdgcn_s_barrier()
;     ...
;     f32x4 acc[2][2][4][2] = {};
;     bf16x8 At[4][2], B0[2][2], B1[2][2];
;     STAGE(SB(0, 0), Bt, bcol, 0); STAGE(SA(0, 0), A, brow, 0);
;     STAGE(SB(0, 1), Bt, bcol + HALF, 0); STAGE(SA(0, 1), A, brow + HALF, 0);
;     if (wr == 1) BAR;
;     WAIT_V(4); BAR;
;     STAGE(SB(1, 0), Bt, bcol, 1); STAGE(SA(1, 0), A, brow, 1); STAGE(SB(1, 1), Bt, bcol + HALF, 1);
;     WAIT_V(6); BAR;
.LBB0_417:
	s_add_u32 s34, s8, 0x80
	s_addc_u32 s35, s9, 0
	s_add_i32 s8, s15, 0x18000
	v_mov_b32_e32 v141, v1
	s_waitcnt vmcnt(4)
	s_barrier
	s_mov_b32 m0, s8
	v_lshl_add_u64 v[4:5], s[34:35], 0, v[0:1]
	s_add_i32 s9, s15, 0x1a000
	global_load_lds_dwordx4 v[4:5], off
	v_lshl_add_u64 v[4:5], s[34:35], 0, v[140:141]
	s_add_u32 s34, s18, 0x80
	s_mov_b32 m0, s9
	s_addc_u32 s35, s19, 0
	s_add_i32 s18, s15, 0x8000
	global_load_lds_dwordx4 v[4:5], off
	s_mov_b32 m0, s18
	v_lshl_add_u64 v[4:5], s[34:35], 0, v[0:1]
	s_add_i32 s19, s15, 0xa000
	global_load_lds_dwordx4 v[4:5], off
	v_lshl_add_u64 v[4:5], s[34:35], 0, v[140:141]
	s_add_u32 s34, s20, 0x80
	s_mov_b32 m0, s19
	s_addc_u32 s35, s21, 0
	s_add_i32 s20, s15, 0x1c000
	global_load_lds_dwordx4 v[4:5], off
	s_mov_b32 m0, s20
	v_lshl_add_u64 v[4:5], s[34:35], 0, v[0:1]
	s_add_i32 s21, s15, 0x1e000
	global_load_lds_dwordx4 v[4:5], off
	v_lshl_add_u64 v[4:5], s[34:35], 0, v[140:141]
	s_mov_b32 m0, s21
	v_and_b32_e32 v3, 15, v2
	global_load_lds_dwordx4 v[4:5], off
	v_and_b32_e32 v6, 48, v2
	v_lshlrev_b32_e32 v2, 2, v2
	v_lshlrev_b32_e32 v4, 6, v3
	v_and_b32_e32 v2, 32, v2
	v_bitop3_b32 v142, v4, v2, v6 bitop3:0x36
	v_or_b32_e32 v2, s33, v3
	v_lshlrev_b32_e32 v4, 6, v2
	v_lshlrev_b32_e32 v2, 2, v2
	v_and_b32_e32 v4, 0x3c0, v4
	v_and_b32_e32 v2, 32, v2
	v_readlane_b32 s34, v245, 36
	v_bitop3_b32 v4, v4, v2, v6 bitop3:0x36
	s_lshl_b32 s30, s30, 11
	v_or_b32_e32 v2, s34, v3
	v_lshlrev_b32_e32 v5, 6, v2
	v_lshlrev_b32_e32 v2, 2, v2
	v_and_b32_e32 v5, 0x3c0, v5
	v_and_b32_e32 v2, 32, v2
	v_readlane_b32 s34, v245, 37
	v_bitop3_b32 v5, v5, v2, v6 bitop3:0x36
	s_lshl_b32 s31, s31, 8
	v_or_b32_e32 v2, s34, v3
	v_lshlrev_b32_e32 v7, 6, v2
	v_lshlrev_b32_e32 v2, 2, v2
	s_add_i32 s30, s30, s31
	v_and_b32_e32 v7, 0x3c0, v7
	v_and_b32_e32 v2, 32, v2
	s_ashr_i32 s31, s30, 31
	v_bitop3_b32 v7, v7, v2, v6 bitop3:0x36
	v_or_b32_e32 v2, s85, v3
	s_lshl_b64 s[30:31], s[30:31], 12
	v_readlane_b32 s37, v244, 19
	v_lshlrev_b32_e32 v3, 6, v2
	v_lshlrev_b32_e32 v2, 2, v2
	s_add_u32 s30, s74, s30
	v_add_u32_e32 v133, s37, v4
	v_readlane_b32 s37, v244, 20
	v_mov_b32_e32 v8, 0
	v_mov_b32_e32 v9, 0
	v_mov_b32_e32 v10, 0
	v_mov_b32_e32 v11, 0
	v_mov_b32_e32 v12, 0
	v_mov_b32_e32 v13, 0
	v_mov_b32_e32 v14, 0
	v_mov_b32_e32 v15, 0
	v_mov_b32_e32 v16, 0
	v_mov_b32_e32 v17, 0
	v_mov_b32_e32 v18, 0
	v_mov_b32_e32 v19, 0
	v_mov_b32_e32 v20, 0
	v_mov_b32_e32 v21, 0
	v_mov_b32_e32 v22, 0
	v_mov_b32_e32 v23, 0
	v_mov_b32_e32 v24, 0
	v_mov_b32_e32 v25, 0
	v_mov_b32_e32 v26, 0
	v_mov_b32_e32 v27, 0
	v_mov_b32_e32 v28, 0
	v_mov_b32_e32 v29, 0
	v_mov_b32_e32 v30, 0
	v_mov_b32_e32 v31, 0
	v_mov_b32_e32 v32, 0
	v_mov_b32_e32 v33, 0
	v_mov_b32_e32 v34, 0
	v_mov_b32_e32 v35, 0
	v_mov_b32_e32 v36, 0
	v_mov_b32_e32 v37, 0
	v_mov_b32_e32 v38, 0
	v_mov_b32_e32 v39, 0
	v_mov_b32_e32 v40, 0
	v_mov_b32_e32 v41, 0
	v_mov_b32_e32 v42, 0
	v_mov_b32_e32 v43, 0
	v_mov_b32_e32 v44, 0
	v_mov_b32_e32 v45, 0
	v_mov_b32_e32 v46, 0
	v_mov_b32_e32 v47, 0
	v_mov_b32_e32 v48, 0
	v_mov_b32_e32 v49, 0
	v_mov_b32_e32 v50, 0
	v_mov_b32_e32 v51, 0
	v_mov_b32_e32 v52, 0
	v_mov_b32_e32 v53, 0
	v_mov_b32_e32 v54, 0
	v_mov_b32_e32 v55, 0
	v_mov_b32_e32 v56, 0
	v_mov_b32_e32 v57, 0
	v_mov_b32_e32 v58, 0
	v_mov_b32_e32 v59, 0
	v_mov_b32_e32 v60, 0
	v_mov_b32_e32 v61, 0
	v_mov_b32_e32 v62, 0
	v_mov_b32_e32 v63, 0
	v_mov_b32_e32 v64, 0
	v_mov_b32_e32 v65, 0
	v_mov_b32_e32 v66, 0
	v_mov_b32_e32 v67, 0
	v_mov_b32_e32 v68, 0
	v_mov_b32_e32 v69, 0
	v_mov_b32_e32 v70, 0
	v_mov_b32_e32 v71, 0
	v_mov_b32_e32 v72, 0
	v_mov_b32_e32 v73, 0
	v_mov_b32_e32 v74, 0
	v_mov_b32_e32 v75, 0
	v_mov_b32_e32 v76, 0
	v_mov_b32_e32 v77, 0
	v_mov_b32_e32 v78, 0
	v_mov_b32_e32 v79, 0
	v_mov_b32_e32 v80, 0
	v_mov_b32_e32 v81, 0
	v_mov_b32_e32 v82, 0
	v_mov_b32_e32 v83, 0
	v_mov_b32_e32 v84, 0
	v_mov_b32_e32 v85, 0
	v_mov_b32_e32 v86, 0
	v_mov_b32_e32 v87, 0
	v_mov_b32_e32 v88, 0
	v_mov_b32_e32 v89, 0
	v_mov_b32_e32 v90, 0
	v_mov_b32_e32 v91, 0
	v_mov_b32_e32 v92, 0
	v_mov_b32_e32 v93, 0
	v_mov_b32_e32 v94, 0
	v_mov_b32_e32 v95, 0
	v_mov_b32_e32 v96, 0
	v_mov_b32_e32 v97, 0
	v_mov_b32_e32 v98, 0
	v_mov_b32_e32 v99, 0
	v_mov_b32_e32 v100, 0
	v_mov_b32_e32 v101, 0
	v_mov_b32_e32 v102, 0
	v_mov_b32_e32 v103, 0
	v_mov_b32_e32 v104, 0
	v_mov_b32_e32 v105, 0
	v_mov_b32_e32 v106, 0
	v_mov_b32_e32 v107, 0
	v_mov_b32_e32 v108, 0
	v_mov_b32_e32 v109, 0
	v_mov_b32_e32 v110, 0
	v_mov_b32_e32 v111, 0
	v_mov_b32_e32 v112, 0
	v_mov_b32_e32 v113, 0
	v_mov_b32_e32 v114, 0
	v_mov_b32_e32 v115, 0
	v_mov_b32_e32 v116, 0
	v_mov_b32_e32 v117, 0
	v_mov_b32_e32 v118, 0
	v_mov_b32_e32 v119, 0
	v_mov_b32_e32 v120, 0
	v_mov_b32_e32 v121, 0
	v_mov_b32_e32 v122, 0
	v_mov_b32_e32 v123, 0
	v_mov_b32_e32 v124, 0
	v_mov_b32_e32 v125, 0
	v_mov_b32_e32 v126, 0
	v_mov_b32_e32 v127, 0
	v_mov_b32_e32 v128, 0
	v_mov_b32_e32 v129, 0
	s_waitcnt vmcnt(6)
	v_and_b32_e32 v3, 0x3c0, v3
	v_and_b32_e32 v2, 32, v2
	s_addc_u32 s31, s75, s31
	v_add_u32_e32 v134, s37, v5
	v_readlane_b32 s37, v244, 21
	v_bitop3_b32 v3, v3, v2, v6 bitop3:0x36
	s_add_u32 s34, s38, s6
	v_mov_b32_e32 v2, 0
	v_add_u32_e32 v137, s37, v7
	v_readlane_b32 s37, v244, 22
	s_addc_u32 s35, s39, s7
	s_mov_b32 s36, -2
	s_mov_b64 s[6:7], 0
	v_add_u32_e32 v139, s37, v3
	v_mov_b32_e32 v3, v2
	v_mov_b32_e32 v4, v2
	v_mov_b32_e32 v5, v2
	v_mov_b32_e32 v6, v2
	v_mov_b32_e32 v7, v2
	s_barrier
